# nt hint also on the read-once epilogue loads: P5 gates, P6 and P8 LayerNorm residual rows
# baseline (speedup 1.0000x reference)
; __device__ __forceinline__ u32x4 pack8(const f32x4 a, const f32x4 b) { u32x4 w; w.x = cvt_pk_bf16(a[0], a[1]); w.y = cvt_pk_bf16(a[2], a[3]); w.z = cvt_pk_bf16(b[0], b[1]); w.w = cvt_pk_bf16(b[2], b[3]); return w; }
;     __device__ __forceinline__ bool carry(f32x4 (&acc)[2][2][4][2], const Unit& u, int wr, int wc, int fr, int fq) const {
;         const int row0 = u.pm * BM + wr * 64 + fr, col0 = u.pn * BM + wc * 32 + 8 * fq; const bool second = u.k0 != 0;
;         u32x4 wg[2][4][2];
;         const bf16_t* gbase = gab + (second ? 1024 : 0);
; #pragma unroll
;         for (int ai = 0; ai < 2; ++ai)
; #pragma unroll
;             for (int m = 0; m < 4; ++m) { const bf16_t* gp = gbase + (size_t)(row0 + ai * HALF + m * 16) * 2048 + col0;
; #pragma unroll
;                 for (int bj = 0; bj < 2; ++bj) wg[ai][m][bj] = *(const u32x4*)(gp + bj * HALF); }
;         asm volatile("" ::: "memory");
; #pragma unroll
;         for (int ai = 0; ai < 2; ++ai) {
; #pragma unroll
;             for (int m = 0; m < 4; ++m) { const int r = row0 + ai * HALF + m * 16;
; #pragma unroll
;                 for (int bj = 0; bj < 2; ++bj) { f32x4 g0, g1; unpack8(wg[ai][m][bj], g0, g1);
;                     if (!second) { acc[ai][bj][m][0] *= g0; acc[ai][bj][m][1] *= g1; }
;                     else *(u32x4*)(mrg + (size_t)r * 1024 + col0 + bj * HALF) = pack8(acc[ai][bj][m][0] * g0, acc[ai][bj][m][1] * g1); } }
.LBB0_966:
	s_cmp_lg_u32 s7, 0
	v_lshl_add_u32 v82, s48, 8, v1
	s_cselect_b64 s[48:49], -1, 0
	s_cmp_eq_u32 s7, 0
	v_lshl_or_b32 v4, s6, 8, v236
	s_cselect_b64 s[6:7], -1, 0
	s_and_b64 vcc, s[6:7], exec
	s_cselect_b32 s6, 0, 0x800
	s_add_u32 s6, s54, s6
	s_addc_u32 s7, s55, 0
	v_ashrrev_i32_e32 v5, 31, v4
	v_ashrrev_i32_e32 v83, 31, v82
	v_lshl_add_u64 v[84:85], v[4:5], 1, s[6:7]
	v_lshlrev_b64 v[78:79], 12, v[82:83]
	v_or_b32_e32 v230, 16, v82
	v_lshl_add_u64 v[102:103], v[84:85], 0, v[78:79]
	v_ashrrev_i32_e32 v231, 31, v230
	global_load_dwordx4 v[78:81], v[102:103], off nt
	global_load_dwordx4 v[106:109], v[102:103], off offset:256 nt
	v_lshlrev_b64 v[102:103], 12, v[230:231]
	v_or_b32_e32 v228, 32, v82
	v_lshl_add_u64 v[134:135], v[84:85], 0, v[102:103]
	v_ashrrev_i32_e32 v229, 31, v228
	global_load_dwordx4 v[102:105], v[134:135], off nt
	global_load_dwordx4 v[138:141], v[134:135], off offset:256 nt
	v_lshlrev_b64 v[134:135], 12, v[228:229]
	v_or_b32_e32 v226, 48, v82
	v_lshl_add_u64 v[142:143], v[84:85], 0, v[134:135]
	v_ashrrev_i32_e32 v227, 31, v226
	global_load_dwordx4 v[134:137], v[142:143], off nt
	global_load_dwordx4 v[166:169], v[142:143], off offset:256 nt
	v_lshlrev_b64 v[142:143], 12, v[226:227]
	v_add_u32_e32 v224, 0x80, v82
	v_lshl_add_u64 v[142:143], v[84:85], 0, v[142:143]
	v_ashrrev_i32_e32 v225, 31, v224
	global_load_dwordx4 v[158:161], v[142:143], off nt
	global_load_dwordx4 v[198:201], v[142:143], off offset:256 nt
	v_lshlrev_b64 v[142:143], 12, v[224:225]
	v_add_u32_e32 v222, 0x90, v82
	v_lshl_add_u64 v[142:143], v[84:85], 0, v[142:143]
	v_ashrrev_i32_e32 v223, 31, v222
	global_load_dwordx4 v[194:197], v[142:143], off nt
	global_load_dwordx4 v[190:193], v[142:143], off offset:256 nt
	v_lshlrev_b64 v[142:143], 12, v[222:223]
	v_add_u32_e32 v220, 0xa0, v82
	v_lshl_add_u64 v[142:143], v[84:85], 0, v[142:143]
	v_ashrrev_i32_e32 v221, 31, v220
	global_load_dwordx4 v[186:189], v[142:143], off nt
	global_load_dwordx4 v[182:185], v[142:143], off offset:256 nt
	v_lshlrev_b64 v[142:143], 12, v[220:221]
	v_add_u32_e32 v218, 0xb0, v82
	v_lshl_add_u64 v[142:143], v[84:85], 0, v[142:143]
	v_ashrrev_i32_e32 v219, 31, v218
	global_load_dwordx4 v[178:181], v[142:143], off nt
	global_load_dwordx4 v[162:165], v[142:143], off offset:256 nt
	v_lshlrev_b64 v[142:143], 12, v[218:219]
	v_lshl_add_u64 v[84:85], v[84:85], 0, v[142:143]
	global_load_dwordx4 v[154:157], v[84:85], off nt
	global_load_dwordx4 v[142:145], v[84:85], off offset:256 nt
	v_lshlrev_b64 v[82:83], 11, v[82:83]
	v_lshl_add_u64 v[82:83], s[8:9], 0, v[82:83]
	v_lshl_add_u64 v[232:233], v[4:5], 1, v[82:83]
	s_waitcnt vmcnt(0)
	v_lshlrev_b32_e32 v82, 16, v78
	v_and_b32_e32 v83, 0xffff0000, v78
	v_lshlrev_b32_e32 v78, 16, v79
	v_and_b32_e32 v79, 0xffff0000, v79
	v_lshlrev_b32_e32 v238, 16, v80
	v_and_b32_e32 v239, 0xffff0000, v80
	v_lshlrev_b32_e32 v80, 16, v81
	v_and_b32_e32 v81, 0xffff0000, v81
	v_pk_mul_f32 v[84:85], v[92:93], v[78:79]
	v_pk_mul_f32 v[82:83], v[90:91], v[82:83]
	v_pk_mul_f32 v[80:81], v[88:89], v[80:81]
	v_pk_mul_f32 v[78:79], v[86:87], v[238:239]
	s_cbranch_vccnz .LBB0_968
	v_cvt_pk_bf16_f32 v82, v82, v83
	v_cvt_pk_bf16_f32 v83, v84, v85
	v_cvt_pk_bf16_f32 v84, v78, v79
	v_cvt_pk_bf16_f32 v85, v80, v81
	global_store_dwordx4 v[232:233], v[82:85], off
	v_mov_b64_e32 v[78:79], v[86:87]
	v_mov_b64_e32 v[80:81], v[88:89]
	v_mov_b64_e32 v[82:83], v[90:91]
	v_mov_b64_e32 v[84:85], v[92:93]

;     __device__ __forceinline__ void fused(f32x4 (&acc)[2][2][4][2], const Unit& u, int wr, int wc, int fr, int fq, PG8_LAS unsigned char* lds, int wid, int lane) const {
;     ...
;         for (int ai = 0; ai < 2; ++ai) {
;             f32x4 bs[4][2][2];
; #pragma unroll
;             for (int m = 0; m < 4; ++m) { const size_t off = (size_t)(u.pm * BM + ai * HALF + wr * 64 + m * 16 + fr) * ldc + col0;
; #pragma unroll
;                 for (int bj = 0; bj < 2; ++bj) { if (baseb) unpack8(*(const u32x4*)(baseb + off + bj * HALF), bs[m][bj][0], bs[m][bj][1]);
;                     else { bs[m][bj][0] = *(const f32x4*)(base + off + bj * HALF); bs[m][bj][1] = *(const f32x4*)(base + off + bj * HALF + 4); } } }
;             asm volatile("" ::: "memory");
; #pragma unroll
;             for (int m = 0; m < 4; ++m) {
; #pragma unroll
;                 for (int bj = 0; bj < 2; ++bj)
; #pragma unroll
;                     for (int n = 0; n < 2; ++n) acc[ai][bj][m][n] += bs[m][bj][n] * ALPHA;
;                 asm volatile("" : "+v"(acc[ai][0][m][0]), "+v"(acc[ai][0][m][1]), "+v"(acc[ai][1][m][0]), "+v"(acc[ai][1][m][1])); }
.LBB0_1093:
	s_lshl_b32 s7, s10, 8
	s_lshl_b32 s0, s11, 5
	s_lshl_b32 s1, s18, 8
	v_add_u32_e32 v164, s7, v170
	s_or_b32 s0, s1, s0
	v_or_b32_e32 v140, 16, v164
	v_or_b32_e32 v148, 32, v164
	v_and_or_b32 v138, v151, 24, s0
	v_ashrrev_i32_e32 v165, 31, v164
	v_ashrrev_i32_e32 v141, 31, v140
	v_ashrrev_i32_e32 v149, 31, v148
	v_ashrrev_i32_e32 v139, 31, v138
	v_lshlrev_b64 v[126:127], 11, v[164:165]
	v_lshlrev_b64 v[140:141], 11, v[140:141]
	v_lshlrev_b64 v[148:149], 11, v[148:149]
	v_lshl_add_u64 v[126:127], s[20:21], 0, v[126:127]
	v_lshlrev_b64 v[162:163], 1, v[138:139]
	v_lshl_add_u64 v[140:141], s[20:21], 0, v[140:141]
	v_lshl_add_u64 v[148:149], s[20:21], 0, v[148:149]
	v_lshl_add_u64 v[166:167], v[126:127], 0, v[162:163]
	v_lshl_add_u64 v[144:145], v[140:141], 0, v[162:163]
	v_lshl_add_u64 v[148:149], v[148:149], 0, v[162:163]
	s_barrier
	global_load_dwordx4 v[126:129], v[166:167], off nt
	global_load_dwordx4 v[130:133], v[166:167], off offset:256 nt
	global_load_dwordx4 v[140:143], v[144:145], off nt
	s_nop 0
	global_load_dwordx4 v[144:147], v[144:145], off offset:256 nt
	s_nop 0
	global_load_dwordx4 v[152:155], v[148:149], off nt
	global_load_dwordx4 v[156:159], v[148:149], off offset:256 nt
	v_or_b32_e32 v148, 48, v164
	v_ashrrev_i32_e32 v149, 31, v148
	v_lshlrev_b64 v[148:149], 11, v[148:149]
	v_lshl_add_u64 v[148:149], s[20:21], 0, v[148:149]
	v_lshl_add_u64 v[148:149], v[148:149], 0, v[162:163]
	global_load_dwordx4 v[172:175], v[148:149], off nt
	global_load_dwordx4 v[176:179], v[148:149], off offset:256 nt
	s_mov_b32 s6, 0x3f9837f0
	v_cmp_gt_u32_e32 vcc, 16, v234
	s_waitcnt vmcnt(0)
	v_lshlrev_b32_e32 v148, 16, v126
	v_and_b32_e32 v149, 0xffff0000, v126
	v_lshlrev_b32_e32 v126, 16, v127
	v_and_b32_e32 v127, 0xffff0000, v127
	v_lshlrev_b32_e32 v160, 16, v128
	v_and_b32_e32 v161, 0xffff0000, v128
	v_lshlrev_b32_e32 v182, 16, v131
	v_and_b32_e32 v183, 0xffff0000, v131
	v_lshlrev_b32_e32 v184, 16, v132
	v_and_b32_e32 v185, 0xffff0000, v132
	v_lshlrev_b32_e32 v188, 16, v140
	v_and_b32_e32 v189, 0xffff0000, v140
	v_lshlrev_b32_e32 v140, 16, v141
	v_and_b32_e32 v141, 0xffff0000, v141
	v_lshlrev_b32_e32 v194, 16, v146
	v_and_b32_e32 v195, 0xffff0000, v146
	v_lshlrev_b32_e32 v200, 16, v156
	v_and_b32_e32 v201, 0xffff0000, v156
	v_lshlrev_b32_e32 v202, 16, v158
	v_and_b32_e32 v203, 0xffff0000, v158
	v_lshlrev_b32_e32 v204, 16, v172
	v_and_b32_e32 v205, 0xffff0000, v172
	v_lshlrev_b32_e32 v168, 16, v129
	v_and_b32_e32 v169, 0xffff0000, v129
	v_lshlrev_b32_e32 v180, 16, v130
	v_and_b32_e32 v181, 0xffff0000, v130
	v_pk_fma_f32 v[128:129], v[126:127], s[6:7], v[124:125] op_sel_hi:[1,0,1]
	v_pk_fma_f32 v[130:131], v[160:161], s[6:7], v[118:119] op_sel_hi:[1,0,1]
	v_pk_fma_f32 v[124:125], v[182:183], s[6:7], v[108:109] op_sel_hi:[1,0,1]
	v_pk_fma_f32 v[118:119], v[184:185], s[6:7], v[94:95] op_sel_hi:[1,0,1]
	v_pk_fma_f32 v[108:109], v[140:141], s[6:7], v[116:117] op_sel_hi:[1,0,1]
	v_pk_fma_f32 v[94:95], v[194:195], s[6:7], v[82:83] op_sel_hi:[1,0,1]
	v_pk_fma_f32 v[82:83], v[200:201], s[6:7], v[78:79] op_sel_hi:[1,0,1]
	v_pk_fma_f32 v[78:79], v[202:203], s[6:7], v[74:75] op_sel_hi:[1,0,1]
	v_pk_fma_f32 v[74:75], v[204:205], s[6:7], v[110:111] op_sel_hi:[1,0,1]
	v_add_u32_e32 v110, 0x80, v164
	v_add_u32_e32 v140, 0x90, v164
	v_pk_fma_f32 v[126:127], v[148:149], s[6:7], v[122:123] op_sel_hi:[1,0,1]
	v_ashrrev_i32_e32 v111, 31, v110
	v_ashrrev_i32_e32 v141, 31, v140
	v_add_u32_e32 v148, 0xa0, v164
	v_lshlrev_b32_e32 v186, 16, v133
	v_and_b32_e32 v187, 0xffff0000, v133
	v_lshlrev_b32_e32 v190, 16, v142
	v_and_b32_e32 v191, 0xffff0000, v142
	v_lshlrev_b32_e32 v142, 16, v143
	v_and_b32_e32 v143, 0xffff0000, v143
	v_lshlrev_b32_e32 v192, 16, v144
	v_and_b32_e32 v193, 0xffff0000, v144
	v_lshlrev_b32_e32 v144, 16, v145
	v_and_b32_e32 v145, 0xffff0000, v145
	v_lshlrev_b32_e32 v146, 16, v147
	v_and_b32_e32 v147, 0xffff0000, v147
	v_lshlrev_b32_e32 v196, 16, v152
	v_and_b32_e32 v197, 0xffff0000, v152
	v_lshlrev_b32_e32 v152, 16, v153
	v_and_b32_e32 v153, 0xffff0000, v153
	v_lshlrev_b32_e32 v198, 16, v154
	v_and_b32_e32 v199, 0xffff0000, v154
	v_lshlrev_b32_e32 v154, 16, v155
	v_and_b32_e32 v155, 0xffff0000, v155
	v_lshlrev_b32_e32 v156, 16, v157
	v_and_b32_e32 v157, 0xffff0000, v157
	v_lshlrev_b32_e32 v158, 16, v159
	v_and_b32_e32 v159, 0xffff0000, v159
	v_lshlrev_b32_e32 v172, 16, v173
	v_and_b32_e32 v173, 0xffff0000, v173
	v_lshlrev_b32_e32 v206, 16, v174
	v_and_b32_e32 v207, 0xffff0000, v174
	v_lshlrev_b32_e32 v174, 16, v175
	v_and_b32_e32 v175, 0xffff0000, v175
	v_lshlrev_b32_e32 v208, 16, v178
	v_and_b32_e32 v209, 0xffff0000, v178
	v_lshlrev_b32_e32 v178, 16, v179
	v_and_b32_e32 v179, 0xffff0000, v179
	v_lshlrev_b32_e32 v210, 16, v176
	v_and_b32_e32 v211, 0xffff0000, v176
	v_lshlrev_b32_e32 v176, 16, v177
	v_and_b32_e32 v177, 0xffff0000, v177
	v_lshlrev_b64 v[110:111], 11, v[110:111]
	v_lshlrev_b64 v[140:141], 11, v[140:141]
	v_ashrrev_i32_e32 v149, 31, v148
	v_pk_fma_f32 v[132:133], v[168:169], s[6:7], v[120:121] op_sel_hi:[1,0,1]
	v_pk_fma_f32 v[122:123], v[180:181], s[6:7], v[106:107] op_sel_hi:[1,0,1]
	v_pk_fma_f32 v[120:121], v[186:187], s[6:7], v[96:97] op_sel_hi:[1,0,1]
	v_pk_fma_f32 v[106:107], v[188:189], s[6:7], v[114:115] op_sel_hi:[1,0,1]
	v_pk_fma_f32 v[116:117], v[142:143], s[6:7], v[100:101] op_sel_hi:[1,0,1]
	v_pk_fma_f32 v[114:115], v[190:191], s[6:7], v[98:99] op_sel_hi:[1,0,1]
	v_pk_fma_f32 v[100:101], v[144:145], s[6:7], v[92:93] op_sel_hi:[1,0,1]
	v_pk_fma_f32 v[98:99], v[192:193], s[6:7], v[90:91] op_sel_hi:[1,0,1]
	v_pk_fma_f32 v[96:97], v[146:147], s[6:7], v[84:85] op_sel_hi:[1,0,1]
	v_pk_fma_f32 v[92:93], v[152:153], s[6:7], v[136:137] op_sel_hi:[1,0,1]
;     __device__ __forceinline__ bool run(const f32x4 (&v)[2][2][4][2], const Unit& u, int wr, int wc, int fr, int fq, PG8_LAS unsigned char* lds, int wid, int lane) const {
;     ...
;                 float s = 0.f;
; #pragma unroll
;                 for (int bj = 0; bj < 2; ++bj)
; #pragma unroll
;                     for (int n = 0; n < 2; ++n) { const f32x4 x = v[ai][bj][m][n]; s += (x[0] + x[1]) + (x[2] + x[3]); }
;                 s += __shfl_xor(s, 16); s += __shfl_xor(s, 32);
;     __device__ __forceinline__ void fused(f32x4 (&acc)[2][2][4][2], const Unit& u, int wr, int wc, int fr, int fq, PG8_LAS unsigned char* lds, int wid, int lane) const {
;     ...
;         for (int ai = 0; ai < 2; ++ai) {
;             f32x4 bs[4][2][2];
; #pragma unroll
;             for (int m = 0; m < 4; ++m) { const size_t off = (size_t)(u.pm * BM + ai * HALF + wr * 64 + m * 16 + fr) * ldc + col0;
; #pragma unroll
;                 for (int bj = 0; bj < 2; ++bj) { if (baseb) unpack8(*(const u32x4*)(baseb + off + bj * HALF), bs[m][bj][0], bs[m][bj][1]);
;                     else { bs[m][bj][0] = *(const f32x4*)(base + off + bj * HALF); bs[m][bj][1] = *(const f32x4*)(base + off + bj * HALF + 4); } } }
;             asm volatile("" ::: "memory");
; #pragma unroll
;             for (int m = 0; m < 4; ++m) {
; #pragma unroll
;                 for (int bj = 0; bj < 2; ++bj)
; #pragma unroll
;                     for (int n = 0; n < 2; ++n) acc[ai][bj][m][n] += bs[m][bj][n] * ALPHA;
;                 asm volatile("" : "+v"(acc[ai][0][m][0]), "+v"(acc[ai][0][m][1]), "+v"(acc[ai][1][m][0]), "+v"(acc[ai][1][m][1])); }
	v_pk_fma_f32 v[90:91], v[196:197], s[6:7], v[134:135] op_sel_hi:[1,0,1]
	v_pk_fma_f32 v[104:105], v[154:155], s[6:7], v[104:105] op_sel_hi:[1,0,1]
	v_pk_fma_f32 v[102:103], v[198:199], s[6:7], v[102:103] op_sel_hi:[1,0,1]
	v_pk_fma_f32 v[84:85], v[156:157], s[6:7], v[80:81] op_sel_hi:[1,0,1]
	v_pk_fma_f32 v[80:81], v[158:159], s[6:7], v[76:77] op_sel_hi:[1,0,1]
	v_pk_fma_f32 v[76:77], v[172:173], s[6:7], v[112:113] op_sel_hi:[1,0,1]
	v_pk_fma_f32 v[88:89], v[174:175], s[6:7], v[88:89] op_sel_hi:[1,0,1]
	v_pk_fma_f32 v[86:87], v[206:207], s[6:7], v[86:87] op_sel_hi:[1,0,1]
	v_pk_fma_f32 v[72:73], v[176:177], s[6:7], v[72:73] op_sel_hi:[1,0,1]
	v_pk_fma_f32 v[70:71], v[210:211], s[6:7], v[70:71] op_sel_hi:[1,0,1]
	v_pk_fma_f32 v[68:69], v[178:179], s[6:7], v[68:69] op_sel_hi:[1,0,1]
	v_pk_fma_f32 v[66:67], v[208:209], s[6:7], v[66:67] op_sel_hi:[1,0,1]
	v_lshl_add_u64 v[110:111], s[20:21], 0, v[110:111]
	v_lshl_add_u64 v[140:141], s[20:21], 0, v[140:141]
	v_lshlrev_b64 v[148:149], 11, v[148:149]
	v_lshl_add_u64 v[168:169], v[110:111], 0, v[162:163]
	v_lshl_add_u64 v[144:145], v[140:141], 0, v[162:163]
	v_lshl_add_u64 v[148:149], s[20:21], 0, v[148:149]
	global_load_dwordx4 v[110:113], v[168:169], off nt
	global_load_dwordx4 v[134:137], v[168:169], off offset:256 nt
	global_load_dwordx4 v[140:143], v[144:145], off nt
	s_nop 0
	global_load_dwordx4 v[144:147], v[144:145], off offset:256 nt
	v_lshl_add_u64 v[148:149], v[148:149], 0, v[162:163]
	global_load_dwordx4 v[156:159], v[148:149], off nt
	global_load_dwordx4 v[172:175], v[148:149], off offset:256 nt
	v_add_u32_e32 v148, 0xb0, v164
	v_ashrrev_i32_e32 v149, 31, v148
	v_lshlrev_b64 v[148:149], 11, v[148:149]
	v_lshl_add_u64 v[148:149], s[20:21], 0, v[148:149]
	v_lshl_add_u64 v[148:149], v[148:149], 0, v[162:163]
	global_load_dwordx4 v[176:179], v[148:149], off nt
	global_load_dwordx4 v[180:183], v[148:149], off offset:256 nt
	v_lshlrev_b32_e32 v154, 5, v150
	s_waitcnt vmcnt(7)
	v_lshlrev_b32_e32 v184, 16, v112
	v_and_b32_e32 v185, 0xffff0000, v112
	s_waitcnt vmcnt(6)
	v_lshlrev_b32_e32 v192, 16, v136
	v_and_b32_e32 v193, 0xffff0000, v136
	s_waitcnt vmcnt(4)
	v_lshlrev_b32_e32 v204, 16, v144
	v_and_b32_e32 v205, 0xffff0000, v144
	v_lshlrev_b32_e32 v208, 16, v146
	v_and_b32_e32 v209, 0xffff0000, v146
	s_waitcnt vmcnt(3)
	v_lshlrev_b32_e32 v212, 16, v156
	v_and_b32_e32 v213, 0xffff0000, v156
	v_lshlrev_b32_e32 v188, 16, v134
	v_and_b32_e32 v189, 0xffff0000, v134
	v_lshlrev_b32_e32 v190, 16, v135
	v_and_b32_e32 v191, 0xffff0000, v135
	v_pk_fma_f32 v[134:135], v[184:185], s[6:7], v[58:59] op_sel_hi:[1,0,1]
	v_pk_fma_f32 v[58:59], v[192:193], s[6:7], v[42:43] op_sel_hi:[1,0,1]
	v_pk_fma_f32 v[42:43], v[204:205], s[6:7], v[34:35] op_sel_hi:[1,0,1]
	v_pk_fma_f32 v[34:35], v[208:209], s[6:7], v[26:27] op_sel_hi:[1,0,1]
	v_pk_fma_f32 v[26:27], v[212:213], s[6:7], v[38:39] op_sel_hi:[1,0,1]
	v_mbcnt_lo_u32_b32 v38, -1, 0
	v_lshlrev_b32_e32 v186, 16, v113
	v_and_b32_e32 v187, 0xffff0000, v113
	v_lshlrev_b32_e32 v194, 16, v137
	v_and_b32_e32 v195, 0xffff0000, v137
	v_lshlrev_b32_e32 v206, 16, v145
	v_and_b32_e32 v207, 0xffff0000, v145
	v_lshlrev_b32_e32 v210, 16, v147
	v_and_b32_e32 v211, 0xffff0000, v147
	v_lshlrev_b32_e32 v156, 16, v157
	v_and_b32_e32 v157, 0xffff0000, v157
	v_mbcnt_hi_u32_b32 v39, -1, v38
	v_lshlrev_b32_e32 v160, 16, v110
	v_and_b32_e32 v161, 0xffff0000, v110
	v_lshlrev_b32_e32 v110, 16, v111
	v_and_b32_e32 v111, 0xffff0000, v111
	v_lshlrev_b32_e32 v196, 16, v140
	v_and_b32_e32 v197, 0xffff0000, v140
	v_pk_fma_f32 v[136:137], v[186:187], s[6:7], v[60:61] op_sel_hi:[1,0,1]
	v_pk_fma_f32 v[60:61], v[194:195], s[6:7], v[44:45] op_sel_hi:[1,0,1]
	v_pk_fma_f32 v[44:45], v[206:207], s[6:7], v[36:37] op_sel_hi:[1,0,1]
	v_pk_fma_f32 v[36:37], v[210:211], s[6:7], v[28:29] op_sel_hi:[1,0,1]
	v_pk_fma_f32 v[28:29], v[156:157], s[6:7], v[40:41] op_sel_hi:[1,0,1]
	v_and_b32_e32 v40, 64, v39
	v_lshlrev_b32_e32 v198, 16, v141
	v_and_b32_e32 v199, 0xffff0000, v141
	v_pk_fma_f32 v[112:113], v[110:111], s[6:7], v[64:65] op_sel_hi:[1,0,1]
	v_pk_fma_f32 v[110:111], v[160:161], s[6:7], v[62:63] op_sel_hi:[1,0,1]
	v_pk_fma_f32 v[62:63], v[188:189], s[6:7], v[50:51] op_sel_hi:[1,0,1]
	v_pk_fma_f32 v[50:51], v[196:197], s[6:7], v[54:55] op_sel_hi:[1,0,1]
	v_add_u32_e32 v155, 64, v40
	v_mov_b32_e32 v40, v127
	v_mov_b32_e32 v41, v128
	v_mov_b32_e32 v54, v126
	v_mov_b32_e32 v55, v129
	v_pk_fma_f32 v[64:65], v[190:191], s[6:7], v[52:53] op_sel_hi:[1,0,1]
	v_pk_fma_f32 v[52:53], v[198:199], s[6:7], v[56:57] op_sel_hi:[1,0,1]
	v_pk_add_f32 v[40:41], v[40:41], v[54:55]
	v_mov_b32_e32 v54, v131
	v_mov_b32_e32 v55, v132
	v_mov_b32_e32 v56, v130
	v_mov_b32_e32 v57, v133
	v_pk_add_f32 v[54:55], v[54:55], v[56:57]
	v_add_f32_e32 v40, v40, v41
	v_pk_add_f32 v[54:55], v[54:55], v[54:55] op_sel_hi:[0,1]
	v_xor_b32_e32 v38, 16, v39
	v_add_f32_e32 v41, 0, v40
	v_add_f32_e32 v57, v122, v123
	v_add_f32_e32 v157, v124, v125
	v_mov_b32_e32 v56, v118
	v_mov_b32_e32 v156, v119
	v_mov_b32_e32 v54, v120
	v_mov_b32_e32 v40, v121
	v_cmp_lt_i32_e64 s[0:1], v38, v155
	v_pk_add_f32 v[56:57], v[56:57], v[156:157]
	v_pk_add_f32 v[40:41], v[54:55], v[40:41]
	v_cndmask_b32_e64 v38, v39, v38, s[0:1]
	v_pk_add_f32 v[40:41], v[56:57], v[40:41]
	v_lshlrev_b32_e32 v38, 2, v38
	v_add_f32_e32 v40, v40, v41
	v_mov_b32_e32 v41, v40
	s_nop 1
	v_permlane16_swap_b32_e32 v41, v40
	v_xor_b32_e32 v54, 32, v39
	v_cmp_lt_i32_e64 s[0:1], v54, v155
	v_lshlrev_b32_e32 v200, 16, v142
	v_and_b32_e32 v201, 0xffff0000, v142
	v_cndmask_b32_e64 v39, v39, v54, s[0:1]
	v_lshlrev_b32_e32 v39, 2, v39
	s_waitcnt lgkmcnt(0)
;     __device__ __forceinline__ bool run(const f32x4 (&v)[2][2][4][2], const Unit& u, int wr, int wc, int fr, int fq, PG8_LAS unsigned char* lds, int wid, int lane) const {
;     ...
;                 float s = 0.f;
; #pragma unroll
;                 for (int bj = 0; bj < 2; ++bj)
; #pragma unroll
;                     for (int n = 0; n < 2; ++n) { const f32x4 x = v[ai][bj][m][n]; s += (x[0] + x[1]) + (x[2] + x[3]); }
;                 s += __shfl_xor(s, 16); s += __shfl_xor(s, 32);
;                 const float mw = s * (1.0f / 64.0f); float q = 0.f;
; #pragma unroll
;                 for (int bj = 0; bj < 2; ++bj)
; #pragma unroll
;                     for (int n = 0; n < 2; ++n) { const f32x4 d = v[ai][bj][m][n] - mw; q += (d[0] * d[0] + d[1] * d[1]) + (d[2] * d[2] + d[3] * d[3]); }
;                 q += __shfl_xor(q, 16); q += __shfl_xor(q, 32);
;                 if (fq == 0) P[(ai * HALF + wr * 64 + m * 16 + fr) * 4 + wc] = (f32x2v){mw, q};
	v_add_f32_e32 v40, v40, v41
	v_mov_b32_e32 v41, v40
	s_nop 1
	v_permlane32_swap_b32_e32 v41, v40
	v_lshlrev_b32_e32 v202, 16, v143
	v_and_b32_e32 v203, 0xffff0000, v143
	v_lshlrev_b32_e32 v214, 16, v158
	v_and_b32_e32 v215, 0xffff0000, v158
	s_waitcnt lgkmcnt(0)
	v_add_f32_e32 v40, v40, v41
	v_fmamk_f32 v54, v40, 0xbc800000, v129
	v_fmamk_f32 v56, v40, 0xbc800000, v127
	v_fmamk_f32 v41, v40, 0xbc800000, v128
	v_fmamk_f32 v55, v40, 0xbc800000, v126
	v_mul_f32_e32 v56, v56, v56
	v_mul_f32_e32 v54, v54, v54
	v_fmac_f32_e32 v56, v55, v55
	v_fmac_f32_e32 v54, v41, v41
	v_fmamk_f32 v55, v40, 0xbc800000, v133
	v_fmamk_f32 v57, v40, 0xbc800000, v131
	v_add_f32_e32 v41, v56, v54
	v_fmamk_f32 v54, v40, 0xbc800000, v132
	v_fmamk_f32 v56, v40, 0xbc800000, v130
	v_mul_f32_e32 v57, v57, v57
	v_mul_f32_e32 v55, v55, v55
	v_fmac_f32_e32 v57, v56, v56
	v_fmac_f32_e32 v55, v54, v54
	v_add_f32_e32 v54, v57, v55
	v_fmamk_f32 v55, v40, 0xbc800000, v125
	v_fmamk_f32 v57, v40, 0xbc800000, v123
	v_add_f32_e32 v41, v41, v54
	v_fmamk_f32 v54, v40, 0xbc800000, v124
	v_fmamk_f32 v56, v40, 0xbc800000, v122
	v_mul_f32_e32 v57, v57, v57
	v_mul_f32_e32 v55, v55, v55
	v_fmac_f32_e32 v57, v56, v56
	v_fmac_f32_e32 v55, v54, v54
	v_add_f32_e32 v54, v57, v55
	v_fmamk_f32 v55, v40, 0xbc800000, v121
	v_fmamk_f32 v57, v40, 0xbc800000, v119
	v_add_f32_e32 v41, v54, v41
	v_fmamk_f32 v54, v40, 0xbc800000, v120
	v_fmamk_f32 v56, v40, 0xbc800000, v118
	v_mul_f32_e32 v57, v57, v57
	v_mul_f32_e32 v55, v55, v55
	v_fmac_f32_e32 v57, v56, v56
	v_fmac_f32_e32 v55, v54, v54
	v_add_f32_e32 v54, v57, v55
	v_add_f32_e32 v41, v54, v41
	v_mov_b32_e32 v54, v41
	s_nop 1
	v_permlane16_swap_b32_e32 v54, v41
	v_lshlrev_b32_e32 v158, 16, v159
	v_and_b32_e32 v159, 0xffff0000, v159
	s_waitcnt vmcnt(2)
	v_lshlrev_b32_e32 v216, 16, v172
	v_and_b32_e32 v217, 0xffff0000, v172
	s_waitcnt lgkmcnt(0)
	v_add_f32_e32 v41, v41, v54
	v_lshlrev_b32_e32 v172, 16, v173
	v_and_b32_e32 v173, 0xffff0000, v173
	v_lshlrev_b32_e32 v218, 16, v174
	v_and_b32_e32 v219, 0xffff0000, v174
	v_lshlrev_b32_e32 v174, 16, v175
	v_and_b32_e32 v175, 0xffff0000, v175
	s_waitcnt vmcnt(1)
	v_lshlrev_b32_e32 v146, 16, v176
	v_and_b32_e32 v147, 0xffff0000, v176
	v_lshlrev_b32_e32 v176, 16, v177
	v_and_b32_e32 v177, 0xffff0000, v177
	v_lshlrev_b32_e32 v148, 16, v178
	v_and_b32_e32 v149, 0xffff0000, v178
	v_lshlrev_b32_e32 v150, 16, v179
	v_and_b32_e32 v151, 0xffff0000, v179
	s_waitcnt vmcnt(0)
	v_lshlrev_b32_e32 v140, 16, v182
	v_and_b32_e32 v141, 0xffff0000, v182
	v_lshlrev_b32_e32 v142, 16, v183
	v_and_b32_e32 v143, 0xffff0000, v183
	v_lshlrev_b32_e32 v144, 16, v180
	v_and_b32_e32 v145, 0xffff0000, v180
	v_lshlrev_b32_e32 v152, 16, v181
	v_and_b32_e32 v153, 0xffff0000, v181
	v_mov_b32_e32 v54, v41
	s_nop 1
	v_permlane32_swap_b32_e32 v54, v41
	v_pk_fma_f32 v[48:49], v[202:203], s[6:7], v[48:49] op_sel_hi:[1,0,1]
	v_pk_fma_f32 v[46:47], v[200:201], s[6:7], v[46:47] op_sel_hi:[1,0,1]
	v_pk_fma_f32 v[32:33], v[158:159], s[6:7], v[32:33] op_sel_hi:[1,0,1]
	v_pk_fma_f32 v[30:31], v[214:215], s[6:7], v[30:31] op_sel_hi:[1,0,1]
	v_pk_fma_f32 v[24:25], v[172:173], s[6:7], v[24:25] op_sel_hi:[1,0,1]
	v_pk_fma_f32 v[22:23], v[216:217], s[6:7], v[22:23] op_sel_hi:[1,0,1]
	v_pk_fma_f32 v[20:21], v[174:175], s[6:7], v[20:21] op_sel_hi:[1,0,1]
	v_pk_fma_f32 v[18:19], v[218:219], s[6:7], v[18:19] op_sel_hi:[1,0,1]
	v_pk_fma_f32 v[16:17], v[176:177], s[6:7], v[16:17] op_sel_hi:[1,0,1]
	v_pk_fma_f32 v[14:15], v[146:147], s[6:7], v[14:15] op_sel_hi:[1,0,1]
	v_pk_fma_f32 v[12:13], v[150:151], s[6:7], v[12:13] op_sel_hi:[1,0,1]
	v_pk_fma_f32 v[10:11], v[148:149], s[6:7], v[10:11] op_sel_hi:[1,0,1]
	v_pk_fma_f32 v[8:9], v[152:153], s[6:7], v[8:9] op_sel_hi:[1,0,1]
	v_pk_fma_f32 v[6:7], v[144:145], s[6:7], v[6:7] op_sel_hi:[1,0,1]
	v_pk_fma_f32 v[4:5], v[142:143], s[6:7], v[4:5] op_sel_hi:[1,0,1]
	v_pk_fma_f32 v[2:3], v[140:141], s[6:7], v[2:3] op_sel_hi:[1,0,1]
	s_lshl_b32 s0, s11, 3
	s_add_i32 s6, s0, 0
	s_and_saveexec_b64 s[0:1], vcc
	s_cbranch_execz .LBB0_1095
	s_lshl_b32 s8, s35, 11
	s_add_i32 s8, s6, s8
	v_mul_f32_e32 v40, 0x3c800000, v40
	v_add_u32_e32 v55, s8, v154
	s_waitcnt lgkmcnt(0)
	v_add_f32_e32 v41, v41, v54
	ds_write_b64 v55, v[40:41]

;     __device__ __forceinline__ void fused(f32x4 (&acc)[2][2][4][2], const Unit& u, int wr, int wc, int fr, int fq, PG8_LAS unsigned char* lds, int wid, int lane) const {
;     ...
;         for (int ai = 0; ai < 2; ++ai) {
;             f32x4 bs[4][2][2];
; #pragma unroll
;             for (int m = 0; m < 4; ++m) { const size_t off = (size_t)(u.pm * BM + ai * HALF + wr * 64 + m * 16 + fr) * ldc + col0;
; #pragma unroll
;                 for (int bj = 0; bj < 2; ++bj) { if (baseb) unpack8(*(const u32x4*)(baseb + off + bj * HALF), bs[m][bj][0], bs[m][bj][1]);
;                     else { bs[m][bj][0] = *(const f32x4*)(base + off + bj * HALF); bs[m][bj][1] = *(const f32x4*)(base + off + bj * HALF + 4); } } }
;             asm volatile("" ::: "memory");
; #pragma unroll
;             for (int m = 0; m < 4; ++m) {
; #pragma unroll
;                 for (int bj = 0; bj < 2; ++bj)
; #pragma unroll
;                     for (int n = 0; n < 2; ++n) acc[ai][bj][m][n] += bs[m][bj][n] * ALPHA;
;                 asm volatile("" : "+v"(acc[ai][0][m][0]), "+v"(acc[ai][0][m][1]), "+v"(acc[ai][1][m][0]), "+v"(acc[ai][1][m][1])); }
.LBB0_1344:
	s_lshl_b32 s0, s7, 5
	s_lshl_b32 s1, s8, 8
	s_lshl_b32 s16, s6, 8
	s_or_b32 s0, s1, s0
	v_add_u32_e32 v164, s16, v170
	v_and_or_b32 v162, v150, 24, s0
	v_ashrrev_i32_e32 v165, 31, v164
	v_ashrrev_i32_e32 v163, 31, v162
	v_lshlrev_b64 v[130:131], 10, v[164:165]
	v_lshl_add_u64 v[168:169], v[130:131], 0, v[162:163]
	v_lshl_add_u64 v[134:135], v[168:169], 1, s[20:21]
	s_barrier
	global_load_dwordx4 v[130:133], v[134:135], off nt
	global_load_dwordx4 v[136:139], v[134:135], off offset:256 nt
	v_or_b32_e32 v134, 16, v164
	v_or_b32_e32 v148, 32, v164
	v_ashrrev_i32_e32 v135, 31, v134
	v_ashrrev_i32_e32 v149, 31, v148
	v_or_b32_e32 v156, 48, v164
	v_lshlrev_b64 v[140:141], 11, v[134:135]
	v_lshlrev_b64 v[148:149], 11, v[148:149]
	v_ashrrev_i32_e32 v157, 31, v156
	v_lshlrev_b64 v[134:135], 1, v[162:163]
	v_lshl_add_u64 v[140:141], s[20:21], 0, v[140:141]
	v_lshl_add_u64 v[148:149], s[20:21], 0, v[148:149]
	v_lshlrev_b64 v[156:157], 11, v[156:157]
	v_lshl_add_u64 v[144:145], v[140:141], 0, v[134:135]
	v_lshl_add_u64 v[152:153], v[148:149], 0, v[134:135]
	v_lshl_add_u64 v[156:157], s[20:21], 0, v[156:157]
	global_load_dwordx4 v[140:143], v[144:145], off nt
	s_nop 0
	global_load_dwordx4 v[144:147], v[144:145], off offset:256 nt
	s_nop 0
	global_load_dwordx4 v[148:151], v[152:153], off nt
	s_nop 0
	global_load_dwordx4 v[152:155], v[152:153], off offset:256 nt
	v_lshl_add_u64 v[160:161], v[156:157], 0, v[134:135]
	global_load_dwordx4 v[156:159], v[160:161], off nt
	global_load_dwordx4 v[172:175], v[160:161], off offset:256 nt
	s_mov_b32 s0, 0x3f9837f0
	s_waitcnt vmcnt(0)
	v_lshlrev_b32_e32 v160, 16, v130
	v_and_b32_e32 v161, 0xffff0000, v130
	v_lshlrev_b32_e32 v130, 16, v131
	v_and_b32_e32 v131, 0xffff0000, v131
	v_lshlrev_b32_e32 v166, 16, v132
	v_and_b32_e32 v167, 0xffff0000, v132
	v_lshlrev_b32_e32 v132, 16, v133
	v_and_b32_e32 v133, 0xffff0000, v133
	v_lshlrev_b32_e32 v178, 16, v138
	v_and_b32_e32 v179, 0xffff0000, v138
	v_lshlrev_b32_e32 v138, 16, v139
	v_and_b32_e32 v139, 0xffff0000, v139
	v_pk_fma_f32 v[124:125], v[130:131], s[0:1], v[124:125] op_sel_hi:[1,0,1]
	v_pk_fma_f32 v[132:133], v[132:133], s[0:1], v[128:129] op_sel_hi:[1,0,1]
	v_pk_fma_f32 v[130:131], v[166:167], s[0:1], v[126:127] op_sel_hi:[1,0,1]
	v_pk_fma_f32 v[128:129], v[138:139], s[0:1], v[104:105] op_sel_hi:[1,0,1]
	v_lshlrev_b32_e32 v180, 16, v140
	v_and_b32_e32 v181, 0xffff0000, v140
	v_lshlrev_b32_e32 v140, 16, v141
	v_and_b32_e32 v141, 0xffff0000, v141
	v_lshlrev_b32_e32 v182, 16, v142
	v_and_b32_e32 v183, 0xffff0000, v142
	v_lshlrev_b32_e32 v186, 16, v146
	v_and_b32_e32 v187, 0xffff0000, v146
	v_lshlrev_b32_e32 v188, 16, v148
	v_and_b32_e32 v189, 0xffff0000, v148
	v_lshlrev_b32_e32 v190, 16, v150
	v_and_b32_e32 v191, 0xffff0000, v150
	v_lshlrev_b32_e32 v194, 16, v154
	v_and_b32_e32 v195, 0xffff0000, v154
	v_lshlrev_b32_e32 v196, 16, v156
	v_and_b32_e32 v197, 0xffff0000, v156
	v_lshlrev_b32_e32 v142, 16, v143
	v_and_b32_e32 v143, 0xffff0000, v143
	v_lshlrev_b32_e32 v146, 16, v147
	v_and_b32_e32 v147, 0xffff0000, v147
	v_lshlrev_b32_e32 v148, 16, v149
	v_and_b32_e32 v149, 0xffff0000, v149
	v_pk_fma_f32 v[126:127], v[178:179], s[0:1], v[102:103] op_sel_hi:[1,0,1]
	v_pk_fma_f32 v[104:105], v[140:141], s[0:1], v[120:121] op_sel_hi:[1,0,1]
	v_pk_fma_f32 v[102:103], v[180:181], s[0:1], v[118:119] op_sel_hi:[1,0,1]
	v_pk_fma_f32 v[118:119], v[182:183], s[0:1], v[106:107] op_sel_hi:[1,0,1]
	v_pk_fma_f32 v[106:107], v[186:187], s[0:1], v[86:87] op_sel_hi:[1,0,1]
	v_pk_fma_f32 v[86:87], v[188:189], s[0:1], v[98:99] op_sel_hi:[1,0,1]
	v_pk_fma_f32 v[98:99], v[190:191], s[0:1], v[90:91] op_sel_hi:[1,0,1]
	v_pk_fma_f32 v[90:91], v[194:195], s[0:1], v[70:71] op_sel_hi:[1,0,1]
	v_pk_fma_f32 v[70:71], v[196:197], s[0:1], v[110:111] op_sel_hi:[1,0,1]
	v_add_u32_e32 v110, 0x80, v164
	v_add_u32_e32 v140, 0x90, v164
	v_pk_fma_f32 v[120:121], v[142:143], s[0:1], v[108:109] op_sel_hi:[1,0,1]
	v_pk_fma_f32 v[108:109], v[146:147], s[0:1], v[88:89] op_sel_hi:[1,0,1]
	v_pk_fma_f32 v[88:89], v[148:149], s[0:1], v[100:101] op_sel_hi:[1,0,1]
	v_ashrrev_i32_e32 v111, 31, v110
	v_ashrrev_i32_e32 v141, 31, v140
	v_add_u32_e32 v148, 0xa0, v164
	v_lshlrev_b32_e32 v176, 16, v136
	v_and_b32_e32 v177, 0xffff0000, v136
	v_lshlrev_b32_e32 v136, 16, v137
	v_and_b32_e32 v137, 0xffff0000, v137
	v_lshlrev_b32_e32 v184, 16, v144
	v_and_b32_e32 v185, 0xffff0000, v144
	v_lshlrev_b32_e32 v144, 16, v145
	v_and_b32_e32 v145, 0xffff0000, v145
	v_lshlrev_b32_e32 v150, 16, v151
	v_and_b32_e32 v151, 0xffff0000, v151
	v_lshlrev_b32_e32 v192, 16, v152
	v_and_b32_e32 v193, 0xffff0000, v152
	v_lshlrev_b32_e32 v152, 16, v153
	v_and_b32_e32 v153, 0xffff0000, v153
	v_lshlrev_b32_e32 v154, 16, v155
	v_and_b32_e32 v155, 0xffff0000, v155
	v_lshlrev_b32_e32 v156, 16, v157
	v_and_b32_e32 v157, 0xffff0000, v157
	v_lshlrev_b32_e32 v198, 16, v158
	v_and_b32_e32 v199, 0xffff0000, v158
	v_lshlrev_b32_e32 v158, 16, v159
	v_and_b32_e32 v159, 0xffff0000, v159
	v_lshlrev_b32_e32 v200, 16, v174
	v_and_b32_e32 v201, 0xffff0000, v174
	v_lshlrev_b32_e32 v174, 16, v175
	v_and_b32_e32 v175, 0xffff0000, v175
	v_lshlrev_b32_e32 v202, 16, v172
	v_and_b32_e32 v203, 0xffff0000, v172
	v_lshlrev_b32_e32 v172, 16, v173
	v_and_b32_e32 v173, 0xffff0000, v173
	v_lshlrev_b64 v[110:111], 10, v[110:111]
	v_lshlrev_b64 v[140:141], 11, v[140:141]
	v_ashrrev_i32_e32 v149, 31, v148
	v_pk_fma_f32 v[122:123], v[160:161], s[0:1], v[122:123] op_sel_hi:[1,0,1]
	v_pk_fma_f32 v[116:117], v[136:137], s[0:1], v[116:117] op_sel_hi:[1,0,1]
	v_pk_fma_f32 v[114:115], v[176:177], s[0:1], v[114:115] op_sel_hi:[1,0,1]
	v_pk_fma_f32 v[96:97], v[144:145], s[0:1], v[96:97] op_sel_hi:[1,0,1]
;     __device__ __forceinline__ bool run(const f32x4 (&v)[2][2][4][2], const Unit& u, int wr, int wc, int fr, int fq, PG8_LAS unsigned char* lds, int wid, int lane) const {
;     ...
;                 float s = 0.f;
; #pragma unroll
;                 for (int bj = 0; bj < 2; ++bj)
; #pragma unroll
;                     for (int n = 0; n < 2; ++n) { const f32x4 x = v[ai][bj][m][n]; s += (x[0] + x[1]) + (x[2] + x[3]); }
;                 s += __shfl_xor(s, 16); s += __shfl_xor(s, 32);
;     __device__ __forceinline__ void fused(f32x4 (&acc)[2][2][4][2], const Unit& u, int wr, int wc, int fr, int fq, PG8_LAS unsigned char* lds, int wid, int lane) const {
;     ...
;         for (int ai = 0; ai < 2; ++ai) {
;             f32x4 bs[4][2][2];
; #pragma unroll
;             for (int m = 0; m < 4; ++m) { const size_t off = (size_t)(u.pm * BM + ai * HALF + wr * 64 + m * 16 + fr) * ldc + col0;
; #pragma unroll
;                 for (int bj = 0; bj < 2; ++bj) { if (baseb) unpack8(*(const u32x4*)(baseb + off + bj * HALF), bs[m][bj][0], bs[m][bj][1]);
;                     else { bs[m][bj][0] = *(const f32x4*)(base + off + bj * HALF); bs[m][bj][1] = *(const f32x4*)(base + off + bj * HALF + 4); } } }
;             asm volatile("" ::: "memory");
; #pragma unroll
;             for (int m = 0; m < 4; ++m) {
; #pragma unroll
;                 for (int bj = 0; bj < 2; ++bj)
; #pragma unroll
;                     for (int n = 0; n < 2; ++n) acc[ai][bj][m][n] += bs[m][bj][n] * ALPHA;
;                 asm volatile("" : "+v"(acc[ai][0][m][0]), "+v"(acc[ai][0][m][1]), "+v"(acc[ai][1][m][0]), "+v"(acc[ai][1][m][1])); }
	v_pk_fma_f32 v[94:95], v[184:185], s[0:1], v[94:95] op_sel_hi:[1,0,1]
	v_pk_fma_f32 v[100:101], v[150:151], s[0:1], v[92:93] op_sel_hi:[1,0,1]
	v_pk_fma_f32 v[80:81], v[152:153], s[0:1], v[80:81] op_sel_hi:[1,0,1]
	v_pk_fma_f32 v[78:79], v[192:193], s[0:1], v[78:79] op_sel_hi:[1,0,1]
	v_pk_fma_f32 v[92:93], v[154:155], s[0:1], v[72:73] op_sel_hi:[1,0,1]
	v_pk_fma_f32 v[72:73], v[156:157], s[0:1], v[112:113] op_sel_hi:[1,0,1]
	v_pk_fma_f32 v[84:85], v[158:159], s[0:1], v[84:85] op_sel_hi:[1,0,1]
	v_pk_fma_f32 v[82:83], v[198:199], s[0:1], v[82:83] op_sel_hi:[1,0,1]
	v_pk_fma_f32 v[68:69], v[172:173], s[0:1], v[68:69] op_sel_hi:[1,0,1]
	v_pk_fma_f32 v[66:67], v[202:203], s[0:1], v[66:67] op_sel_hi:[1,0,1]
	v_pk_fma_f32 v[76:77], v[174:175], s[0:1], v[76:77] op_sel_hi:[1,0,1]
	v_pk_fma_f32 v[74:75], v[200:201], s[0:1], v[74:75] op_sel_hi:[1,0,1]
	v_lshl_add_u64 v[166:167], v[110:111], 0, v[162:163]
	v_lshl_add_u64 v[140:141], s[20:21], 0, v[140:141]
	v_lshlrev_b64 v[148:149], 11, v[148:149]
	v_lshl_add_u64 v[136:137], v[166:167], 1, s[20:21]
	v_lshl_add_u64 v[144:145], v[140:141], 0, v[134:135]
	v_lshl_add_u64 v[148:149], s[20:21], 0, v[148:149]
	global_load_dwordx4 v[110:113], v[136:137], off nt
	s_nop 0
	global_load_dwordx4 v[136:139], v[136:137], off offset:256 nt
	s_nop 0
	global_load_dwordx4 v[140:143], v[144:145], off nt
	s_nop 0
	global_load_dwordx4 v[144:147], v[144:145], off offset:256 nt
	v_lshl_add_u64 v[152:153], v[148:149], 0, v[134:135]
	global_load_dwordx4 v[148:151], v[152:153], off nt
	s_nop 0
	global_load_dwordx4 v[152:155], v[152:153], off offset:256 nt
	v_add_u32_e32 v156, 0xb0, v164
	v_ashrrev_i32_e32 v157, 31, v156
	v_lshlrev_b64 v[156:157], 11, v[156:157]
	v_lshl_add_u64 v[156:157], s[20:21], 0, v[156:157]
	v_lshl_add_u64 v[134:135], v[156:157], 0, v[134:135]
	global_load_dwordx4 v[156:159], v[134:135], off nt
	global_load_dwordx4 v[172:175], v[134:135], off offset:256 nt
	s_waitcnt vmcnt(7)
	v_lshlrev_b32_e32 v160, 16, v110
	v_and_b32_e32 v161, 0xffff0000, v110
	v_lshlrev_b32_e32 v110, 16, v111
	v_and_b32_e32 v111, 0xffff0000, v111
	v_lshlrev_b32_e32 v176, 16, v112
	v_and_b32_e32 v177, 0xffff0000, v112
	s_waitcnt vmcnt(6)
	v_lshlrev_b32_e32 v182, 16, v138
	v_and_b32_e32 v183, 0xffff0000, v138
	s_waitcnt vmcnt(5)
	v_lshlrev_b32_e32 v186, 16, v140
	v_and_b32_e32 v187, 0xffff0000, v140
	v_lshlrev_b32_e32 v190, 16, v142
	v_and_b32_e32 v191, 0xffff0000, v142
	s_waitcnt vmcnt(4)
	v_lshlrev_b32_e32 v198, 16, v146
	v_and_b32_e32 v199, 0xffff0000, v146
	s_waitcnt vmcnt(3)
	v_lshlrev_b32_e32 v202, 16, v148
	v_and_b32_e32 v203, 0xffff0000, v148
	v_pk_fma_f32 v[64:65], v[110:111], s[0:1], v[64:65] op_sel_hi:[1,0,1]
	v_pk_fma_f32 v[110:111], v[176:177], s[0:1], v[58:59] op_sel_hi:[1,0,1]
	v_pk_fma_f32 v[58:59], v[182:183], s[0:1], v[42:43] op_sel_hi:[1,0,1]
	v_pk_fma_f32 v[42:43], v[186:187], s[0:1], v[54:55] op_sel_hi:[1,0,1]
	v_pk_fma_f32 v[54:55], v[190:191], s[0:1], v[46:47] op_sel_hi:[1,0,1]
	v_pk_fma_f32 v[46:47], v[198:199], s[0:1], v[26:27] op_sel_hi:[1,0,1]
	v_pk_fma_f32 v[26:27], v[202:203], s[0:1], v[38:39] op_sel_hi:[1,0,1]
	v_mbcnt_lo_u32_b32 v38, -1, 0
	v_lshlrev_b32_e32 v112, 16, v113
	v_and_b32_e32 v113, 0xffff0000, v113
	v_lshlrev_b32_e32 v184, 16, v139
	v_and_b32_e32 v185, 0xffff0000, v139
	v_lshlrev_b32_e32 v188, 16, v141
	v_and_b32_e32 v189, 0xffff0000, v141
	v_lshlrev_b32_e32 v192, 16, v143
	v_and_b32_e32 v193, 0xffff0000, v143
	v_lshlrev_b32_e32 v200, 16, v147
	v_and_b32_e32 v201, 0xffff0000, v147
	v_lshlrev_b32_e32 v148, 16, v149
	v_and_b32_e32 v149, 0xffff0000, v149
	v_mbcnt_hi_u32_b32 v39, -1, v38
	s_waitcnt vmcnt(2)
	v_lshlrev_b32_e32 v208, 16, v154
	v_and_b32_e32 v209, 0xffff0000, v154
	v_lshlrev_b32_e32 v154, 16, v155
	v_and_b32_e32 v155, 0xffff0000, v155
	v_pk_fma_f32 v[112:113], v[112:113], s[0:1], v[60:61] op_sel_hi:[1,0,1]
	v_pk_fma_f32 v[60:61], v[184:185], s[0:1], v[44:45] op_sel_hi:[1,0,1]
	v_pk_fma_f32 v[44:45], v[188:189], s[0:1], v[56:57] op_sel_hi:[1,0,1]
	v_pk_fma_f32 v[56:57], v[192:193], s[0:1], v[48:49] op_sel_hi:[1,0,1]
	v_pk_fma_f32 v[48:49], v[200:201], s[0:1], v[28:29] op_sel_hi:[1,0,1]
	v_pk_fma_f32 v[28:29], v[148:149], s[0:1], v[40:41] op_sel_hi:[1,0,1]
	v_and_b32_e32 v40, 64, v39
	v_lshlrev_b32_e32 v204, 16, v150
	v_and_b32_e32 v205, 0xffff0000, v150
	v_lshlrev_b32_e32 v150, 16, v151
	v_and_b32_e32 v151, 0xffff0000, v151
	v_pk_fma_f32 v[20:21], v[154:155], s[0:1], v[20:21] op_sel_hi:[1,0,1]
	v_add_u32_e32 v154, 64, v40
	v_mov_b32_e32 v40, v123
	v_mov_b32_e32 v41, v124
	v_mov_b32_e32 v148, v122
	v_mov_b32_e32 v149, v125
	v_pk_fma_f32 v[32:33], v[150:151], s[0:1], v[32:33] op_sel_hi:[1,0,1]
	v_pk_add_f32 v[40:41], v[40:41], v[148:149]
	v_mov_b32_e32 v148, v131
	v_mov_b32_e32 v149, v132
	v_mov_b32_e32 v150, v130
	v_mov_b32_e32 v151, v133
	v_pk_add_f32 v[148:149], v[148:149], v[150:151]
	v_lshlrev_b32_e32 v206, 16, v152
	v_and_b32_e32 v207, 0xffff0000, v152
	v_lshlrev_b32_e32 v152, 16, v153
	v_and_b32_e32 v153, 0xffff0000, v153
	v_add_f32_e32 v40, v40, v41
	v_pk_add_f32 v[148:149], v[148:149], v[148:149] op_sel_hi:[0,1]
	v_pk_fma_f32 v[24:25], v[152:153], s[0:1], v[24:25] op_sel_hi:[1,0,1]
	v_xor_b32_e32 v38, 16, v39
	v_add_f32_e32 v41, 0, v40
	v_add_f32_e32 v151, v114, v115
	v_add_f32_e32 v153, v116, v117
	v_mov_b32_e32 v150, v126
	v_mov_b32_e32 v152, v127
	v_mov_b32_e32 v148, v128
	v_mov_b32_e32 v40, v129
	v_cmp_lt_i32_e32 vcc, v38, v154
	v_pk_add_f32 v[150:151], v[150:151], v[152:153]
	v_pk_add_f32 v[40:41], v[148:149], v[40:41]
	v_cndmask_b32_e32 v38, v39, v38, vcc
	v_pk_add_f32 v[40:41], v[150:151], v[40:41]
	v_lshlrev_b32_e32 v38, 2, v38
	v_add_f32_e32 v40, v40, v41
	v_mov_b32_e32 v41, v40
	s_nop 1
	v_permlane16_swap_b32_e32 v41, v40
	v_xor_b32_e32 v148, 32, v39
	v_cmp_lt_i32_e32 vcc, v148, v154
	s_waitcnt vmcnt(1)
;     __device__ __forceinline__ bool run(const f32x4 (&v)[2][2][4][2], const Unit& u, int wr, int wc, int fr, int fq, PG8_LAS unsigned char* lds, int wid, int lane) const {
;     ...
;                 float s = 0.f;
; #pragma unroll
;                 for (int bj = 0; bj < 2; ++bj)
; #pragma unroll
;                     for (int n = 0; n < 2; ++n) { const f32x4 x = v[ai][bj][m][n]; s += (x[0] + x[1]) + (x[2] + x[3]); }
;                 s += __shfl_xor(s, 16); s += __shfl_xor(s, 32);
;                 const float mw = s * (1.0f / 64.0f); float q = 0.f;
; #pragma unroll
;                 for (int bj = 0; bj < 2; ++bj)
; #pragma unroll
;                     for (int n = 0; n < 2; ++n) { const f32x4 d = v[ai][bj][m][n] - mw; q += (d[0] * d[0] + d[1] * d[1]) + (d[2] * d[2] + d[3] * d[3]); }
;                 q += __shfl_xor(q, 16); q += __shfl_xor(q, 32);
;                 if (fq == 0) P[(ai * HALF + wr * 64 + m * 16 + fr) * 4 + wc] = (f32x2v){mw, q};
	v_lshlrev_b32_e32 v140, 16, v156
	v_and_b32_e32 v141, 0xffff0000, v156
	v_cndmask_b32_e32 v39, v39, v148, vcc
	v_lshlrev_b32_e32 v39, 2, v39
	s_waitcnt lgkmcnt(0)
	v_add_f32_e32 v40, v40, v41
	v_mov_b32_e32 v41, v40
	s_nop 1
	v_permlane32_swap_b32_e32 v41, v40
	v_lshlrev_b32_e32 v142, 16, v158
	v_and_b32_e32 v143, 0xffff0000, v158
	v_pk_fma_f32 v[14:15], v[140:141], s[0:1], v[14:15] op_sel_hi:[1,0,1]
	v_pk_fma_f32 v[10:11], v[142:143], s[0:1], v[10:11] op_sel_hi:[1,0,1]
	s_waitcnt lgkmcnt(0)
	v_add_f32_e32 v40, v40, v41
	v_fmamk_f32 v140, v40, 0xbc800000, v125
	v_fmamk_f32 v142, v40, 0xbc800000, v123
	v_fmamk_f32 v41, v40, 0xbc800000, v124
	v_fmamk_f32 v141, v40, 0xbc800000, v122
	v_mul_f32_e32 v142, v142, v142
	v_mul_f32_e32 v140, v140, v140
	v_fmac_f32_e32 v142, v141, v141
	v_fmac_f32_e32 v140, v41, v41
	v_fmamk_f32 v141, v40, 0xbc800000, v133
	v_fmamk_f32 v143, v40, 0xbc800000, v131
	v_add_f32_e32 v41, v142, v140
	v_fmamk_f32 v140, v40, 0xbc800000, v132
	v_fmamk_f32 v142, v40, 0xbc800000, v130
	v_mul_f32_e32 v143, v143, v143
	v_mul_f32_e32 v141, v141, v141
	v_fmac_f32_e32 v143, v142, v142
	v_fmac_f32_e32 v141, v140, v140
	v_add_f32_e32 v140, v143, v141
	v_fmamk_f32 v141, v40, 0xbc800000, v117
	v_fmamk_f32 v143, v40, 0xbc800000, v115
	v_add_f32_e32 v41, v41, v140
	v_fmamk_f32 v140, v40, 0xbc800000, v116
	v_fmamk_f32 v142, v40, 0xbc800000, v114
	v_mul_f32_e32 v143, v143, v143
	v_mul_f32_e32 v141, v141, v141
	v_fmac_f32_e32 v143, v142, v142
	v_fmac_f32_e32 v141, v140, v140
	v_add_f32_e32 v140, v143, v141
	v_fmamk_f32 v141, v40, 0xbc800000, v129
	v_fmamk_f32 v143, v40, 0xbc800000, v127
	v_add_f32_e32 v41, v140, v41
	v_fmamk_f32 v140, v40, 0xbc800000, v128
	v_fmamk_f32 v142, v40, 0xbc800000, v126
	v_mul_f32_e32 v143, v143, v143
	v_mul_f32_e32 v141, v141, v141
	v_fmac_f32_e32 v143, v142, v142
	v_fmac_f32_e32 v141, v140, v140
	v_add_f32_e32 v140, v143, v141
	v_add_f32_e32 v41, v140, v41
	v_mov_b32_e32 v140, v41
	s_nop 1
	v_permlane16_swap_b32_e32 v140, v41
	s_waitcnt vmcnt(0)
	v_lshlrev_b32_e32 v134, 16, v174
	v_and_b32_e32 v135, 0xffff0000, v174
	v_lshlrev_b32_e32 v178, 16, v136
	v_and_b32_e32 v179, 0xffff0000, v136
	s_waitcnt lgkmcnt(0)
	v_add_f32_e32 v41, v41, v140
	v_lshlrev_b32_e32 v180, 16, v137
	v_and_b32_e32 v181, 0xffff0000, v137
	v_lshlrev_b32_e32 v194, 16, v144
	v_and_b32_e32 v195, 0xffff0000, v144
	v_lshlrev_b32_e32 v196, 16, v145
	v_and_b32_e32 v197, 0xffff0000, v145
	v_lshlrev_b32_e32 v156, 16, v157
	v_and_b32_e32 v157, 0xffff0000, v157
	v_lshlrev_b32_e32 v144, 16, v159
	v_and_b32_e32 v145, 0xffff0000, v159
	v_lshlrev_b32_e32 v136, 16, v175
	v_and_b32_e32 v137, 0xffff0000, v175
	v_lshlrev_b32_e32 v138, 16, v172
	v_and_b32_e32 v139, 0xffff0000, v172
	v_lshlrev_b32_e32 v146, 16, v173
	v_and_b32_e32 v147, 0xffff0000, v173
	v_pk_fma_f32 v[2:3], v[134:135], s[0:1], v[2:3] op_sel_hi:[1,0,1]
	v_mov_b32_e32 v134, v41
	s_nop 1
	v_permlane32_swap_b32_e32 v134, v41
	v_pk_fma_f32 v[62:63], v[160:161], s[0:1], v[62:63] op_sel_hi:[1,0,1]
	v_pk_fma_f32 v[52:53], v[180:181], s[0:1], v[52:53] op_sel_hi:[1,0,1]
	v_pk_fma_f32 v[50:51], v[178:179], s[0:1], v[50:51] op_sel_hi:[1,0,1]
	v_pk_fma_f32 v[36:37], v[196:197], s[0:1], v[36:37] op_sel_hi:[1,0,1]
	v_pk_fma_f32 v[34:35], v[194:195], s[0:1], v[34:35] op_sel_hi:[1,0,1]
	v_pk_fma_f32 v[30:31], v[204:205], s[0:1], v[30:31] op_sel_hi:[1,0,1]
	v_pk_fma_f32 v[22:23], v[206:207], s[0:1], v[22:23] op_sel_hi:[1,0,1]
	v_pk_fma_f32 v[18:19], v[208:209], s[0:1], v[18:19] op_sel_hi:[1,0,1]
	v_pk_fma_f32 v[16:17], v[156:157], s[0:1], v[16:17] op_sel_hi:[1,0,1]
	v_pk_fma_f32 v[12:13], v[144:145], s[0:1], v[12:13] op_sel_hi:[1,0,1]
	v_pk_fma_f32 v[8:9], v[146:147], s[0:1], v[8:9] op_sel_hi:[1,0,1]
	v_pk_fma_f32 v[6:7], v[138:139], s[0:1], v[6:7] op_sel_hi:[1,0,1]
	v_pk_fma_f32 v[4:5], v[136:137], s[0:1], v[4:5] op_sel_hi:[1,0,1]
	s_lshl_b32 s0, s7, 3
	v_cmp_gt_u32_e32 vcc, 16, v234
	s_add_i32 s2, s0, 0
	s_and_saveexec_b64 s[0:1], vcc
	s_cbranch_execz .LBB0_1346
	s_lshl_b32 s4, s9, 11
	s_add_i32 s4, s2, s4
	v_mul_f32_e32 v40, 0x3c800000, v40
	v_lshl_add_u32 v135, v1, 5, s4
	s_waitcnt lgkmcnt(0)
	v_add_f32_e32 v41, v41, v134
	ds_write_b64 v135, v[40:41]
